# KS=4 meta-row skinny GEMMs (GOUT/GIN/GUP): all 12 operand loads issued before the first MFMA; GOUT also hoists scale loads and batches the LDS reduction reads
# baseline (speedup 1.0000x reference)
.LBB0_93:
	v_add_u32_e32 v2, s19, v143
	v_ashrrev_i32_e32 v3, 31, v2
	v_lshlrev_b64 v[2:3], 11, v[2:3]
	v_lshl_add_u64 v[40:41], v[12:13], 0, v[2:3]
	v_add_u32_e32 v6, s18, v143
	v_ashrrev_i32_e32 v7, 31, v6
	v_lshlrev_b64 v[6:7], 11, v[6:7]
	v_lshl_add_u64 v[42:43], v[12:13], 0, v[6:7]
	global_load_dwordx4 v[44:47], v[40:41], off
	global_load_dwordx4 v[48:51], v[10:11], off
	global_load_dwordx4 v[52:55], v[42:43], off
	global_load_dwordx4 v[56:59], v[40:41], off offset:64
	global_load_dwordx4 v[60:63], v[10:11], off offset:64
	global_load_dwordx4 v[64:67], v[42:43], off offset:64
	global_load_dwordx4 v[68:71], v[40:41], off offset:128
	global_load_dwordx4 v[72:75], v[10:11], off offset:128
	global_load_dwordx4 v[76:79], v[42:43], off offset:128
	global_load_dwordx4 v[80:83], v[40:41], off offset:192
	global_load_dwordx4 v[84:87], v[10:11], off offset:192
	global_load_dwordx4 v[88:91], v[42:43], off offset:192
	s_andn2_b64 vcc, exec, s[38:39]
	s_waitcnt vmcnt(10)
	v_mfma_f32_16x16x32_bf16 v[2:5], v[44:47], v[48:51], 0
	s_waitcnt vmcnt(9)
	v_mfma_f32_16x16x32_bf16 v[6:9], v[52:55], v[48:51], 0
	s_waitcnt vmcnt(7)
	v_mfma_f32_16x16x32_bf16 v[2:5], v[56:59], v[60:63], v[2:5]
	s_waitcnt vmcnt(6)
	v_mfma_f32_16x16x32_bf16 v[6:9], v[64:67], v[60:63], v[6:9]
	s_waitcnt vmcnt(4)
	v_mfma_f32_16x16x32_bf16 v[2:5], v[68:71], v[72:75], v[2:5]
	s_waitcnt vmcnt(3)
	v_mfma_f32_16x16x32_bf16 v[6:9], v[76:79], v[72:75], v[6:9]
	s_waitcnt vmcnt(1)
	v_mfma_f32_16x16x32_bf16 v[2:5], v[80:83], v[84:87], v[2:5]
	s_waitcnt vmcnt(0)
	v_mfma_f32_16x16x32_bf16 v[6:9], v[88:91], v[84:87], v[6:9]
	s_nop 6
	ds_write_b128 v22, v[2:5]
	ds_write_b128 v22, v[6:9] offset:16
	s_waitcnt lgkmcnt(0)
	s_barrier
	s_cbranch_vccnz .LBB0_88
	ds_read_b128 v[24:27], v23 offset:2048
	ds_read_b128 v[28:31], v23 offset:2064
	global_load_dword v20, v[14:15], off
	s_mov_b64 s[42:43], -1
	s_and_b64 vcc, exec, s[26:27]
	s_waitcnt lgkmcnt(1)
	v_pk_add_f32 v[26:27], v[4:5], v[26:27]
	v_pk_add_f32 v[24:25], v[2:3], v[24:25]
	ds_read_b128 v[2:5], v23 offset:4096
	s_waitcnt lgkmcnt(1)
	v_pk_add_f32 v[8:9], v[8:9], v[30:31]
	v_pk_add_f32 v[6:7], v[6:7], v[28:29]
	s_waitcnt lgkmcnt(0)
	v_pk_add_f32 v[26:27], v[26:27], v[4:5]
	v_pk_add_f32 v[24:25], v[24:25], v[2:3]
	ds_read_b128 v[2:5], v23 offset:4112
	s_waitcnt lgkmcnt(0)
	v_pk_add_f32 v[8:9], v[8:9], v[4:5]
	v_pk_add_f32 v[6:7], v[6:7], v[2:3]
	ds_read_b128 v[2:5], v23 offset:6144
	s_waitcnt lgkmcnt(0)
	v_pk_add_f32 v[26:27], v[26:27], v[4:5]
	v_pk_add_f32 v[24:25], v[24:25], v[2:3]
	ds_read_b128 v[2:5], v23 offset:6160
	s_waitcnt lgkmcnt(0)
	v_pk_add_f32 v[8:9], v[8:9], v[4:5]
	v_pk_add_f32 v[6:7], v[6:7], v[2:3]
	ds_read_b128 v[2:5], v23 offset:8192
	s_waitcnt lgkmcnt(0)
	v_pk_add_f32 v[26:27], v[26:27], v[4:5]
	v_pk_add_f32 v[24:25], v[24:25], v[2:3]
	ds_read_b128 v[2:5], v23 offset:8208
	s_waitcnt lgkmcnt(0)
	v_pk_add_f32 v[8:9], v[8:9], v[4:5]
	v_pk_add_f32 v[6:7], v[6:7], v[2:3]
	ds_read_b128 v[2:5], v23 offset:10240
	s_waitcnt lgkmcnt(0)
	v_pk_add_f32 v[26:27], v[26:27], v[4:5]
	v_pk_add_f32 v[24:25], v[24:25], v[2:3]
	ds_read_b128 v[2:5], v23 offset:10256
	s_waitcnt lgkmcnt(0)
	v_pk_add_f32 v[8:9], v[8:9], v[4:5]
	v_pk_add_f32 v[6:7], v[6:7], v[2:3]
	ds_read_b128 v[2:5], v23 offset:12288
	s_waitcnt lgkmcnt(0)
	v_pk_add_f32 v[26:27], v[26:27], v[4:5]
	v_pk_add_f32 v[24:25], v[24:25], v[2:3]
	ds_read_b128 v[2:5], v23 offset:12304
	s_waitcnt lgkmcnt(0)
	v_pk_add_f32 v[8:9], v[8:9], v[4:5]
	v_pk_add_f32 v[28:29], v[6:7], v[2:3]
	ds_read_b128 v[4:7], v23 offset:14336
	s_waitcnt lgkmcnt(0)
	v_pk_add_f32 v[2:3], v[26:27], v[6:7]
	v_pk_add_f32 v[4:5], v[24:25], v[4:5]
	ds_read_b128 v[24:27], v23 offset:14352
	s_waitcnt lgkmcnt(0)
	v_pk_add_f32 v[6:7], v[8:9], v[26:27]
	v_pk_add_f32 v[8:9], v[28:29], v[24:25]
	s_cbranch_vccz .LBB0_96
	s_waitcnt vmcnt(0)
	v_pk_mul_f32 v[24:25], v[2:3], v[20:21] op_sel_hi:[1,0]
	v_pk_mul_f32 v[26:27], v[4:5], v[20:21] op_sel_hi:[1,0]
	v_pk_mul_f32 v[28:29], v[6:7], v[20:21] op_sel_hi:[1,0]
	v_cvt_pk_bf16_f32 v26, v26, v27
	v_cvt_pk_bf16_f32 v27, v24, v25
	v_pk_mul_f32 v[30:31], v[8:9], v[20:21] op_sel_hi:[1,0]
	v_cvt_pk_bf16_f32 v25, v28, v29
	v_add_u32_e32 v28, s15, v21
	v_mov_b32_e32 v29, v1
	v_lshl_add_u64 v[28:29], v[28:29], 1, v[16:17]
	v_cvt_pk_bf16_f32 v24, v30, v31
	global_store_dwordx2 v[28:29], v[26:27], off
	global_store_dwordx2 v[28:29], v[24:25], off offset:32
	s_mov_b64 s[42:43], 0

.LBB0_216:
	v_add_u32_e32 v4, s2, v160
	v_mad_i64_i32 v[2:3], s[18:19], v4, s15, 0
	v_lshl_add_u64 v[36:37], v[2:3], 1, v[12:13]
	v_add_u32_e32 v6, 16, v4
	v_mad_i64_i32 v[6:7], s[18:19], v6, s15, 0
	v_lshl_add_u64 v[38:39], v[6:7], 1, v[12:13]
	global_load_dwordx4 v[40:43], v[36:37], off
	global_load_dwordx4 v[44:47], v[10:11], off
	global_load_dwordx4 v[48:51], v[38:39], off
	global_load_dwordx4 v[52:55], v[36:37], off offset:64
	global_load_dwordx4 v[56:59], v[10:11], off offset:64
	global_load_dwordx4 v[60:63], v[38:39], off offset:64
	global_load_dwordx4 v[64:67], v[36:37], off offset:128
	global_load_dwordx4 v[68:71], v[10:11], off offset:128
	global_load_dwordx4 v[72:75], v[38:39], off offset:128
	global_load_dwordx4 v[76:79], v[36:37], off offset:192
	global_load_dwordx4 v[80:83], v[10:11], off offset:192
	global_load_dwordx4 v[84:87], v[38:39], off offset:192
	v_add_u32_e32 v24, s2, v19
	v_ashrrev_i32_e32 v25, 31, v24
	v_add_u32_e32 v26, 16, v24
	v_ashrrev_i32_e32 v27, 31, v26
	v_lshl_add_u64 v[4:5], v[24:25], 2, s[44:45]
	v_lshl_add_u64 v[6:7], v[26:27], 2, s[44:45]
	global_load_dwordx4 v[28:31], v[4:5], off
	global_load_dwordx4 v[32:35], v[6:7], off
	s_andn2_b64 vcc, exec, s[46:47]
	s_waitcnt vmcnt(12)
	v_mfma_f32_16x16x32_bf16 v[2:5], v[40:43], v[44:47], 0
	s_waitcnt vmcnt(11)
	v_mfma_f32_16x16x32_bf16 v[6:9], v[48:51], v[44:47], 0
	s_waitcnt vmcnt(9)
	v_mfma_f32_16x16x32_bf16 v[2:5], v[52:55], v[56:59], v[2:5]
	s_waitcnt vmcnt(8)
	v_mfma_f32_16x16x32_bf16 v[6:9], v[60:63], v[56:59], v[6:9]
	s_waitcnt vmcnt(6)
	v_mfma_f32_16x16x32_bf16 v[2:5], v[64:67], v[68:71], v[2:5]
	s_waitcnt vmcnt(5)
	v_mfma_f32_16x16x32_bf16 v[6:9], v[72:75], v[68:71], v[6:9]
	s_waitcnt vmcnt(3)
	v_mfma_f32_16x16x32_bf16 v[2:5], v[76:79], v[80:83], v[2:5]
	s_waitcnt vmcnt(2)
	v_mfma_f32_16x16x32_bf16 v[6:9], v[84:87], v[80:83], v[6:9]
	s_nop 6
	ds_write_b128 v0, v[2:5]
	ds_write_b128 v0, v[6:9] offset:16
	s_waitcnt lgkmcnt(0)
	s_barrier
	s_cbranch_vccnz .LBB0_215
	v_add_u32_e32 v17, 0, v18
	ds_read_b128 v[40:43], v17 offset:2048
	ds_read_b128 v[44:47], v17 offset:2064
	ds_read_b128 v[48:51], v17 offset:4096
	ds_read_b128 v[52:55], v17 offset:4112
	ds_read_b128 v[56:59], v17 offset:6144
	ds_read_b128 v[60:63], v17 offset:6160
	ds_read_b128 v[64:67], v17 offset:8192
	ds_read_b128 v[68:71], v17 offset:8208
	ds_read_b128 v[72:75], v17 offset:10240
	ds_read_b128 v[76:79], v17 offset:10256
	ds_read_b128 v[80:83], v17 offset:12288
	ds_read_b128 v[84:87], v17 offset:12304
	ds_read_b128 v[88:91], v17 offset:14336
	ds_read_b128 v[92:95], v17 offset:14352
	s_waitcnt lgkmcnt(13)
	v_pk_add_f32 v[22:23], v[4:5], v[42:43]
	v_pk_add_f32 v[20:21], v[2:3], v[40:41]
	s_waitcnt lgkmcnt(12)
	v_pk_add_f32 v[8:9], v[8:9], v[46:47]
	v_pk_add_f32 v[6:7], v[6:7], v[44:45]
	s_waitcnt lgkmcnt(11)
	v_pk_add_f32 v[22:23], v[22:23], v[50:51]
	v_pk_add_f32 v[20:21], v[20:21], v[48:49]
	s_waitcnt lgkmcnt(10)
	v_pk_add_f32 v[8:9], v[8:9], v[54:55]
	v_pk_add_f32 v[6:7], v[6:7], v[52:53]
	s_waitcnt lgkmcnt(9)
	v_pk_add_f32 v[22:23], v[22:23], v[58:59]
	v_pk_add_f32 v[20:21], v[20:21], v[56:57]
	s_waitcnt lgkmcnt(8)
	v_pk_add_f32 v[8:9], v[8:9], v[62:63]
	v_pk_add_f32 v[6:7], v[6:7], v[60:61]
	s_waitcnt lgkmcnt(7)
	v_pk_add_f32 v[22:23], v[22:23], v[66:67]
	v_pk_add_f32 v[20:21], v[20:21], v[64:65]
	s_waitcnt lgkmcnt(6)
	v_pk_add_f32 v[8:9], v[8:9], v[70:71]
	v_pk_add_f32 v[6:7], v[6:7], v[68:69]
	s_waitcnt lgkmcnt(5)
	v_pk_add_f32 v[22:23], v[22:23], v[74:75]
	v_pk_add_f32 v[20:21], v[20:21], v[72:73]
	s_waitcnt lgkmcnt(4)
	v_pk_add_f32 v[8:9], v[8:9], v[78:79]
	v_pk_add_f32 v[6:7], v[6:7], v[76:77]
	s_waitcnt lgkmcnt(3)
	v_pk_add_f32 v[22:23], v[22:23], v[82:83]
	v_pk_add_f32 v[20:21], v[20:21], v[80:81]
	s_waitcnt lgkmcnt(2)
	v_pk_add_f32 v[8:9], v[8:9], v[86:87]
	v_pk_add_f32 v[6:7], v[6:7], v[84:85]
	s_waitcnt lgkmcnt(1)
	v_pk_add_f32 v[22:23], v[22:23], v[90:91]
	v_pk_add_f32 v[20:21], v[20:21], v[88:89]
	s_waitcnt lgkmcnt(0)
	v_pk_add_f32 v[8:9], v[8:9], v[94:95]
	v_pk_add_f32 v[6:7], v[6:7], v[92:93]
	v_lshl_add_u64 v[24:25], v[24:25], 1, v[14:15]
	s_waitcnt vmcnt(0)
	v_pk_mul_f32 v[20:21], v[20:21], v[28:29]
	v_pk_mul_f32 v[22:23], v[22:23], v[30:31]
	v_pk_mul_f32 v[2:3], v[6:7], v[32:33]
	v_cvt_pk_bf16_f32 v6, v20, v21
	v_cvt_pk_bf16_f32 v7, v22, v23
	global_store_dwordx2 v[24:25], v[6:7], off
	v_lshl_add_u64 v[6:7], v[26:27], 1, v[14:15]
	v_pk_mul_f32 v[4:5], v[8:9], v[34:35]
	v_cvt_pk_bf16_f32 v8, v2, v3
	v_mul_f32_e32 v3, v3, v3
	v_cvt_pk_bf16_f32 v9, v4, v5
	global_store_dwordx2 v[6:7], v[8:9], off
	v_mul_f32_e32 v6, v21, v21
	v_mul_f32_e32 v7, v23, v23
	v_fmac_f32_e32 v6, v20, v20
	v_fmac_f32_e32 v7, v22, v22
	v_add_f32_e32 v6, v6, v7
	v_fmac_f32_e32 v3, v2, v2
	v_add_f32_e32 v2, v6, v3
	v_mul_f32_e32 v3, v5, v5
	v_fmac_f32_e32 v3, v4, v4
	v_and_b32_e32 v4, 64, v231
	v_add_f32_e32 v2, v3, v2
	v_xor_b32_e32 v3, 16, v231
	v_add_u32_e32 v4, 64, v4
	v_cmp_lt_i32_e32 vcc, v3, v4
	s_nop 1
	v_cndmask_b32_e32 v3, v231, v3, vcc
	v_lshlrev_b32_e32 v3, 2, v3
	ds_bpermute_b32 v3, v3, v2
	s_waitcnt lgkmcnt(0)
	v_add_f32_e32 v2, v2, v3
	v_xor_b32_e32 v3, 32, v231
	v_cmp_lt_i32_e32 vcc, v3, v4
	s_nop 1
	v_cndmask_b32_e32 v3, v231, v3, vcc
	v_lshlrev_b32_e32 v3, 2, v3
	ds_bpermute_b32 v3, v3, v2
	s_and_saveexec_b64 s[74:75], s[40:41]
	s_cbranch_execz .LBB0_214
	v_ashrrev_i32_e32 v17, 31, v16
	v_lshl_add_u64 v[4:5], v[16:17], 2, s[26:27]
	s_waitcnt lgkmcnt(0)
	v_add_f32_e32 v2, v2, v3
	global_store_dword v[4:5], v2, off
	s_branch .LBB0_214

.LBB0_277:
	s_and_b32 s18, s15, 0xffffff00
	s_and_b32 s19, s2, 0x70
	s_or_b32 s18, s19, s18
	v_or_b32_e32 v2, s18, v177
	v_ashrrev_i32_e32 v3, 31, v2
	v_lshlrev_b64 v[4:5], 11, v[2:3]
	v_lshl_add_u64 v[32:33], v[20:21], 0, v[4:5]
	v_or_b32_e32 v6, 0x80, v2
	v_ashrrev_i32_e32 v7, 31, v6
	v_lshlrev_b64 v[6:7], 11, v[6:7]
	v_lshl_add_u64 v[42:43], v[20:21], 0, v[6:7]
	global_load_dwordx4 v[44:47], v[32:33], off
	global_load_dwordx4 v[48:51], v[18:19], off
	global_load_dwordx4 v[52:55], v[42:43], off
	global_load_dwordx4 v[56:59], v[32:33], off offset:64
	global_load_dwordx4 v[60:63], v[18:19], off offset:64
	global_load_dwordx4 v[64:67], v[42:43], off offset:64
	global_load_dwordx4 v[68:71], v[32:33], off offset:128
	global_load_dwordx4 v[88:91], v[18:19], off offset:128
	global_load_dwordx4 v[92:95], v[42:43], off offset:128
	global_load_dwordx4 v[96:99], v[32:33], off offset:192
	global_load_dwordx4 v[100:103], v[18:19], off offset:192
	global_load_dwordx4 v[104:107], v[42:43], off offset:192
	s_andn2_b64 vcc, exec, s[26:27]
	s_waitcnt vmcnt(10)
	v_mfma_f32_16x16x32_bf16 v[2:5], v[44:47], v[48:51], 0
	s_waitcnt vmcnt(9)
	v_mfma_f32_16x16x32_bf16 v[6:9], v[52:55], v[48:51], 0
	s_waitcnt vmcnt(7)
	v_mfma_f32_16x16x32_bf16 v[2:5], v[56:59], v[60:63], v[2:5]
	s_waitcnt vmcnt(6)
	v_mfma_f32_16x16x32_bf16 v[6:9], v[64:67], v[60:63], v[6:9]
	s_waitcnt vmcnt(4)
	v_mfma_f32_16x16x32_bf16 v[2:5], v[68:71], v[88:91], v[2:5]
	s_waitcnt vmcnt(3)
	v_mfma_f32_16x16x32_bf16 v[6:9], v[92:95], v[88:91], v[6:9]
	s_waitcnt vmcnt(1)
	v_mfma_f32_16x16x32_bf16 v[2:5], v[96:99], v[100:103], v[2:5]
	s_waitcnt vmcnt(0)
	v_mfma_f32_16x16x32_bf16 v[6:9], v[104:107], v[100:103], v[6:9]
	s_nop 6
	ds_write_b128 v0, v[2:5]
	ds_write_b128 v0, v[6:9] offset:16
	s_waitcnt lgkmcnt(0)
	s_barrier
	s_cbranch_vccnz .LBB0_276
	ds_read_b128 v[10:13], v37 offset:2048
	ds_read_b128 v[14:17], v37 offset:2064
	v_add_u32_e32 v28, s2, v34
	v_ashrrev_i32_e32 v29, 31, v28
	v_and_b32_e32 v38, 64, v231
	s_waitcnt lgkmcnt(1)
	v_pk_add_f32 v[12:13], v[4:5], v[12:13]
	s_waitcnt lgkmcnt(0)
	v_pk_add_f32 v[6:7], v[6:7], v[14:15]
	global_load_dword v14, v[22:23], off
	v_pk_add_f32 v[10:11], v[2:3], v[10:11]
	ds_read_b128 v[2:5], v37 offset:4096
	v_pk_add_f32 v[8:9], v[8:9], v[16:17]
	v_or_b32_e32 v39, v38, v35
	v_or_b32_e32 v38, v38, v36
	v_lshlrev_b32_e32 v42, 2, v39
	s_waitcnt lgkmcnt(0)
	v_pk_add_f32 v[12:13], v[12:13], v[4:5]
	v_pk_add_f32 v[10:11], v[10:11], v[2:3]
	ds_read_b128 v[2:5], v37 offset:4112
	v_lshlrev_b32_e32 v43, 2, v38
	s_waitcnt lgkmcnt(0)
	v_pk_add_f32 v[8:9], v[8:9], v[4:5]
	v_pk_add_f32 v[6:7], v[6:7], v[2:3]
	ds_read_b128 v[2:5], v37 offset:6144
	s_waitcnt lgkmcnt(0)
	v_pk_add_f32 v[12:13], v[12:13], v[4:5]
	v_pk_add_f32 v[10:11], v[10:11], v[2:3]
	ds_read_b128 v[2:5], v37 offset:6160
	s_waitcnt lgkmcnt(0)
	v_pk_add_f32 v[8:9], v[8:9], v[4:5]
	v_pk_add_f32 v[6:7], v[6:7], v[2:3]
	ds_read_b128 v[2:5], v37 offset:8192
	s_waitcnt lgkmcnt(0)
	v_pk_add_f32 v[12:13], v[12:13], v[4:5]
	v_pk_add_f32 v[10:11], v[10:11], v[2:3]
	ds_read_b128 v[2:5], v37 offset:8208
	s_waitcnt lgkmcnt(0)
	v_pk_add_f32 v[8:9], v[8:9], v[4:5]
	v_pk_add_f32 v[6:7], v[6:7], v[2:3]
	ds_read_b128 v[2:5], v37 offset:10240
	s_waitcnt lgkmcnt(0)
	v_pk_add_f32 v[12:13], v[12:13], v[4:5]
	v_pk_add_f32 v[10:11], v[10:11], v[2:3]
	ds_read_b128 v[2:5], v37 offset:10256
	s_waitcnt lgkmcnt(0)
	v_pk_add_f32 v[8:9], v[8:9], v[4:5]
	v_pk_add_f32 v[6:7], v[6:7], v[2:3]
	ds_read_b128 v[2:5], v37 offset:12288
	s_waitcnt lgkmcnt(0)
	v_pk_add_f32 v[12:13], v[12:13], v[4:5]
	v_pk_add_f32 v[10:11], v[10:11], v[2:3]
	ds_read_b128 v[2:5], v37 offset:12304
	s_waitcnt lgkmcnt(0)
	v_pk_add_f32 v[8:9], v[8:9], v[4:5]
	v_pk_add_f32 v[6:7], v[6:7], v[2:3]
	ds_read_b128 v[2:5], v37 offset:14336
	s_waitcnt lgkmcnt(0)
	v_pk_add_f32 v[12:13], v[12:13], v[4:5]
	v_pk_add_f32 v[10:11], v[10:11], v[2:3]
	ds_read_b128 v[2:5], v37 offset:14352
	s_waitcnt lgkmcnt(0)
	v_pk_add_f32 v[8:9], v[8:9], v[4:5]
	v_pk_add_f32 v[6:7], v[6:7], v[2:3]
	s_waitcnt vmcnt(0)
	v_pk_mul_f32 v[4:5], v[12:13], v[14:15] op_sel_hi:[1,0]
	v_pk_mul_f32 v[2:3], v[10:11], v[14:15] op_sel_hi:[1,0]
	v_pk_mul_f32 v[30:31], v[8:9], v[14:15] op_sel_hi:[1,0]
	v_pk_mul_f32 v[32:33], v[6:7], v[14:15] op_sel_hi:[1,0]
	v_lshlrev_b64 v[14:15], 2, v[28:29]
	v_lshl_add_u64 v[6:7], s[44:45], 0, v[14:15]
	v_lshl_add_u64 v[10:11], s[50:51], 0, v[14:15]
	v_lshl_add_u64 v[14:15], s[62:63], 0, v[14:15]
	global_load_dwordx4 v[6:9], v[6:7], off
	ds_bpermute_b32 v38, v42, v2
	global_load_dwordx4 v[10:13], v[10:11], off
	ds_bpermute_b32 v40, v43, v2
	global_load_dwordx4 v[14:17], v[14:15], off
	s_waitcnt lgkmcnt(1)
	v_cndmask_b32_e64 v39, v38, 0, s[38:39]
	v_mov_b32_e32 v38, v2
	s_waitcnt lgkmcnt(0)
	v_cndmask_b32_e64 v44, 0, v40, s[40:41]
	s_waitcnt vmcnt(1)
	v_mov_b32_e32 v41, v10
	s_waitcnt vmcnt(0)
	v_mov_b32_e32 v40, v14
	v_pk_mul_f32 v[38:39], v[40:41], v[38:39]
	s_nop 0
	v_fma_f32 v6, v6, v44, v39
	v_add_f32_e32 v6, v38, v6
	v_mul_f32_e32 v10, 0xbfb8aa3b, v6
	v_exp_f32_e32 v10, v10
	v_mov_b32_e32 v38, v3
	v_add_f32_e32 v10, 1.0, v10
	v_rcp_f32_e32 v10, v10
	s_nop 0
	v_mul_f32_e32 v6, v6, v10
	v_mul_f32_e32 v14, v32, v6
	ds_bpermute_b32 v6, v42, v3
	ds_bpermute_b32 v10, v43, v3
	s_waitcnt lgkmcnt(1)
	v_cndmask_b32_e64 v39, v6, 0, s[38:39]
	s_waitcnt lgkmcnt(0)
	v_cndmask_b32_e64 v6, 0, v10, s[40:41]
	v_mov_b32_e32 v10, v15
	v_pk_mul_f32 v[10:11], v[10:11], v[38:39]
	s_nop 0
	v_fma_f32 v6, v7, v6, v11
	v_add_f32_e32 v6, v10, v6
	v_mul_f32_e32 v7, 0xbfb8aa3b, v6
	v_exp_f32_e32 v7, v7
	ds_bpermute_b32 v10, v43, v4
	v_mov_b32_e32 v11, v12
	v_mov_b32_e32 v12, v17
	v_add_f32_e32 v7, 1.0, v7
	v_rcp_f32_e32 v7, v7
	s_waitcnt lgkmcnt(0)
	v_cndmask_b32_e64 v32, 0, v10, s[40:41]
	v_mov_b32_e32 v10, v16
	v_mul_f32_e32 v6, v6, v7
	v_mul_f32_e32 v15, v33, v6
	ds_bpermute_b32 v6, v42, v4
	s_waitcnt lgkmcnt(0)
	v_cndmask_b32_e64 v7, v6, 0, s[38:39]
	v_mov_b32_e32 v6, v4
	v_pk_mul_f32 v[6:7], v[10:11], v[6:7]
	ds_bpermute_b32 v10, v43, v5
	v_fma_f32 v7, v8, v32, v7
	v_add_f32_e32 v6, v6, v7
	v_mul_f32_e32 v7, 0xbfb8aa3b, v6
	v_exp_f32_e32 v7, v7
	s_waitcnt lgkmcnt(0)
	v_cndmask_b32_e64 v10, 0, v10, s[40:41]
	v_add_f32_e32 v7, 1.0, v7
	v_rcp_f32_e32 v7, v7
	s_nop 0
	v_mul_f32_e32 v6, v6, v7
	v_mul_f32_e32 v8, v30, v6
	ds_bpermute_b32 v6, v42, v5
	s_waitcnt lgkmcnt(0)
	v_cndmask_b32_e64 v7, v6, 0, s[38:39]
	v_mov_b32_e32 v6, v5
	v_pk_mul_f32 v[6:7], v[12:13], v[6:7]
	s_nop 0
	v_fma_f32 v7, v9, v10, v7
	v_add_f32_e32 v6, v6, v7
	v_mul_f32_e32 v7, 0xbfb8aa3b, v6
	v_exp_f32_e32 v7, v7
	s_nop 0
	v_add_f32_e32 v7, 1.0, v7
	v_rcp_f32_e32 v7, v7
	s_nop 0
	v_mul_f32_e32 v6, v6, v7
	v_mul_f32_e32 v7, v31, v6
	v_cvt_pk_bf16_f32 v7, v8, v7
	v_lshl_add_u64 v[8:9], v[28:29], 1, v[24:25]
	v_cvt_pk_bf16_f32 v6, v14, v15
	global_store_dwordx2 v[8:9], v[6:7], off
	s_and_saveexec_b64 s[46:47], s[42:43]
	s_cbranch_execz .LBB0_275
	v_lshl_add_u64 v[6:7], v[28:29], 2, v[26:27]
	global_store_dwordx4 v[6:7], v[2:5], off
	s_branch .LBB0_275
